# v068 + in-projection phase start: LDS staging of row scales / q,k gains deferred behind the first LDS-DMA loads
# speedup vs baseline: 1.0221x; 1.0004x over previous
.LBB0_212:
	v_mov_b32_e32 v205, 0
	s_cmp_lt_i32 s56, 0
	v_readlane_b32 s18, v255, 8
	s_cselect_b64 s[16:17], -1, 0
	v_readlane_b32 s19, v255, 9
	s_or_b64 s[16:17], s[16:17], s[18:19]
	s_mov_b64 s[18:19], 0
	s_and_saveexec_b64 s[20:21], s[16:17]
	s_xor_b64 s[16:17], exec, s[20:21]
	s_cbranch_execz .LBB0_345
	s_mov_b64 s[58:59], 0
	s_mov_b64 s[18:19], exec
	v_readlane_b32 s20, v255, 2
	v_readlane_b32 s21, v255, 3
	s_and_b64 s[20:21], s[18:19], s[20:21]
	s_xor_b64 s[18:19], s[20:21], s[18:19]
	s_mov_b64 exec, s[20:21]
	s_cbranch_execz .LBB0_219
	v_lshl_add_u32 v2, s5, 6, v0
	s_mov_b64 s[20:21], exec
	v_readlane_b32 s34, v255, 4
	v_readlane_b32 s35, v255, 5
	s_and_b64 s[34:35], s[20:21], s[34:35]
	s_xor_b64 s[58:59], s[34:35], s[20:21]
	s_mov_b64 exec, s[34:35]
	s_cbranch_execz .LBB0_216
	s_load_dwordx2 s[20:21], s[10:11], 0x20
	s_waitcnt lgkmcnt(0)
	v_lshl_add_u64 v[206:207], v[2:3], 2, s[20:21]
	global_load_dword v200, v[206:207], off offset:-1280
	v_mov_b32_e32 v205, 1
.LBB0_216:
	s_andn2_saveexec_b64 s[58:59], s[58:59]
	s_cbranch_execz .LBB0_218
	s_load_dwordx2 s[10:11], s[10:11], 0x18
	s_waitcnt lgkmcnt(0)
	v_lshl_add_u64 v[208:209], v[2:3], 2, s[10:11]
	global_load_dword v200, v[208:209], off offset:-1024
	v_mov_b32_e32 v205, 2

.LBB0_221:
.LBB0_222:
	s_or_b64 exec, exec, s[10:11]
	v_mov_b32_e32 v12, v0
	v_cndmask_b32_e64 v2, 0, 1, s[14:15]
	s_waitcnt lgkmcnt(0)
	s_barrier
	v_cmp_ne_u32_e64 s[10:11], 1, v2
	s_andn2_b64 vcc, exec, s[14:15]
	v_readfirstlane_b32 s6, v12
	s_cbranch_vccnz .LBB0_224
	s_ashr_i32 s4, s54, 31
	s_lshr_b32 s4, s4, 29
	s_add_i32 s4, s54, s4
	s_ashr_i32 s9, s4, 3
	s_and_b32 s4, s4, -8
	s_sub_i32 s4, s54, s4
	s_cmp_lt_i32 s4, 0
	s_movk_i32 s14, 0x51
	s_cselect_b32 s14, s14, 0x50
	s_mul_i32 s4, s4, s14
	s_add_i32 s4, s4, s9
	s_mul_hi_i32 s9, s4, 0x66666667
	s_lshr_b32 s14, s9, 31
	s_ashr_i32 s9, s9, 5
	s_add_i32 s9, s9, s14
	s_lshl_b32 s14, s9, 3
	s_mulk_i32 s9, 0x50
	s_sub_i32 s4, s4, s9
	s_bfe_i32 s9, s4, 0x80000
	s_bfe_u32 s9, s9, 0x3000c
	s_add_i32 s9, s4, s9
	s_bfe_i32 s15, s9, 0x80000
	s_and_b32 s9, s9, 0xf8
	s_sub_i32 s4, s4, s9
	s_sext_i32_i16 s15, s15
	s_sext_i32_i8 s4, s4
	s_add_i32 s16, s14, s4
	s_ashr_i32 s14, s15, 3

.LBB0_227:
	s_add_u32 s60, s12, 0x5400000
	s_addc_u32 s61, s13, 0
	s_add_u32 s62, s12, 0x100000
	s_addc_u32 s63, s13, 0
	s_add_u32 s64, s12, 0x200000
	s_addc_u32 s65, s13, 0
	s_and_b32 s21, s10, 3
	s_add_i32 m0, s35, 0x18000
	v_lshl_add_u64 v[10:11], v[10:11], 0, s[30:31]
	s_lshl_b32 s12, s24, 13
	s_lshl_b32 s13, s21, 12
	s_waitcnt vmcnt(2)
	s_barrier
	v_cmp_eq_u32_e64 s[98:99], 3, v205
	s_nop 3
	s_and_saveexec_b64 s[100:101], s[98:99]
	v_mov_b32_e32 v206, v201
	v_mov_b32_e32 v207, v202
	v_mov_b32_e32 v201, v203
	v_pk_add_f32 v[200:201], v[206:207], v[200:201]
	s_nop 0
	v_add_f32_e32 v200, v200, v201
	v_fmamk_f32 v200, v200, 0x3a800000, v193
	v_rsq_f32_e32 v200, v200
	s_or_b64 exec, exec, s[100:101]
	v_cmp_eq_u32_e64 s[98:99], 2, v205
	s_nop 3
	s_and_saveexec_b64 s[100:101], s[98:99]
	v_mul_f32_e32 v200, 0x3e38aa3b, v200
	s_or_b64 exec, exec, s[100:101]
	v_cmp_ne_u32_e64 s[98:99], 0, v205
	s_nop 3
	s_and_saveexec_b64 s[100:101], s[98:99]
	ds_write_b32 v194, v200
	s_or_b64 exec, exec, s[100:101]
	global_load_lds_dwordx4 v[10:11], off
	v_lshl_add_u64 v[8:9], v[8:9], 0, s[30:31]
	s_add_i32 m0, s35, 0x1a000
	s_add_i32 s82, s35, 0x8000
	s_add_i32 s27, s35, 0xa000
	global_load_lds_dwordx4 v[8:9], off
	v_lshl_add_u64 v[4:5], v[4:5], 0, s[30:31]
	s_mov_b32 m0, s82
	s_add_u32 s10, s76, 0x40080
	global_load_lds_dwordx4 v[4:5], off
	v_lshl_add_u64 v[4:5], v[6:7], 0, s[30:31]
	s_mov_b32 m0, s27
	s_addc_u32 s11, s77, 0
	global_load_lds_dwordx4 v[4:5], off
	s_add_i32 m0, s35, 0x1c000
	v_lshl_add_u64 v[4:5], s[10:11], 0, v[2:3]
	global_load_lds_dwordx4 v[4:5], off
	v_lshl_add_u64 v[4:5], s[10:11], 0, v[152:153]
	s_add_i32 m0, s35, 0x1e000
	s_cmpk_lt_u32 s6, 0x100
	global_load_lds_dwordx4 v[4:5], off
	v_bfe_u32 v5, v12, 4, 2
	v_and_b32_e32 v4, 15, v12
	v_lshlrev_b32_e32 v7, 4, v5
	v_readlane_b32 s6, v255, 10
	v_lshl_or_b32 v166, s24, 6, v4
	v_lshl_or_b32 v7, v4, 6, v7
	v_lshlrev_b32_e32 v4, 2, v4
	s_cselect_b64 s[66:67], -1, 0
	v_lshl_add_u32 v203, v5, 5, s6
	s_lshl_b32 s6, s24, 8
	v_and_b32_e32 v8, 32, v4
	s_add_i32 s6, s6, 0
	v_bitop3_b32 v9, v7, s12, v8 bitop3:0xde
	s_add_i32 s12, s6, 0x20000
	s_add_i32 s6, s6, 0x20200
	v_add_u32_e32 v204, s12, v4
	v_add_u32_e32 v205, s6, v4
	v_lshlrev_b32_e32 v4, 14, v13
	v_and_b32_e32 v4, 0xffff8000, v4
	v_lshlrev_b32_e32 v6, 3, v5
	v_cmp_eq_u32_e64 s[10:11], 0, v5
	v_lshl_add_u32 v4, v14, 11, v4
	v_and_b32_e32 v5, 1, v13
	v_lshl_or_b32 v4, v5, 6, v4
	v_lshl_add_u32 v154, v15, 1, v4
	v_lshlrev_b32_e32 v4, 14, v16
	v_and_b32_e32 v4, 0xffff8000, v4
	s_waitcnt vmcnt(6)
	v_lshl_add_u32 v4, v17, 11, v4
	v_and_b32_e32 v5, 1, v16
	v_lshl_or_b32 v4, v5, 6, v4
	v_bitop3_b32 v184, v7, s13, v8 bitop3:0xde
	v_lshl_or_b32 v185, s21, 6, v6
	s_mov_b32 s80, 0
	v_or_b32_e32 v186, 16, v166
	v_or_b32_e32 v187, 32, v166
	v_or_b32_e32 v188, 48, v166
	v_add_u32_e32 v189, 0x80, v166
	v_add_u32_e32 v200, 0x90, v166
	v_add_u32_e32 v201, 0xa0, v166
	v_add_u32_e32 v202, 0xb0, v166
	s_ashr_i32 s89, s8, 31
	v_mov_b32_e32 v155, v3
	v_lshl_add_u32 v156, v18, 1, v4
	v_mov_b32_e32 v157, v3
	v_add_u32_e32 v206, 0, v9
	s_barrier
	s_branch .LBB0_230

.LBB0_346:
	v_lshl_or_b32 v2, s56, 8, v0
	v_lshl_add_u64 v[210:211], v[2:3], 4, s[12:13]
	v_add_co_u32_e32 v210, vcc, 0x100000, v210
	s_or_b64 s[18:19], s[18:19], exec
	s_nop 0
	v_addc_co_u32_e32 v211, vcc, 0, v211, vcc
	global_load_dwordx4 v[200:203], v[210:211], off
	v_mov_b32_e32 v205, 3
	s_or_b64 exec, exec, s[10:11]
	s_and_saveexec_b64 s[10:11], s[18:19]
	s_cbranch_execnz .LBB0_221
	s_branch .LBB0_222

	.amdhsa_kernel _Z14fwd_megakernel4Args
		.amdhsa_group_segment_fixed_size 0
		.amdhsa_private_segment_fixed_size 0
		.amdhsa_kernarg_size 392
		.amdhsa_user_sgpr_count 2
		.amdhsa_user_sgpr_dispatch_ptr 0
		.amdhsa_user_sgpr_queue_ptr 0
		.amdhsa_user_sgpr_kernarg_segment_ptr 1
		.amdhsa_user_sgpr_dispatch_id 0
		.amdhsa_user_sgpr_kernarg_preload_length 0
		.amdhsa_user_sgpr_kernarg_preload_offset 0
		.amdhsa_user_sgpr_private_segment_size 0
		.amdhsa_uses_dynamic_stack 0
		.amdhsa_enable_private_segment 0
		.amdhsa_system_sgpr_workgroup_id_x 1
		.amdhsa_system_sgpr_workgroup_id_y 0
		.amdhsa_system_sgpr_workgroup_id_z 0
		.amdhsa_system_sgpr_workgroup_info 0
		.amdhsa_system_vgpr_workitem_id 0
		.amdhsa_next_free_vgpr 256
		.amdhsa_next_free_sgpr 102
		.amdhsa_accum_offset 256
		.amdhsa_reserve_vcc 1
		.amdhsa_float_round_mode_32 0
		.amdhsa_float_round_mode_16_64 0
		.amdhsa_float_denorm_mode_32 3
		.amdhsa_float_denorm_mode_16_64 3
		.amdhsa_dx10_clamp 1
		.amdhsa_ieee_mode 1
		.amdhsa_fp16_overflow 0
		.amdhsa_tg_split 0
		.amdhsa_exception_fp_ieee_invalid_op 0
		.amdhsa_exception_fp_denorm_src 0
		.amdhsa_exception_fp_ieee_div_zero 0
		.amdhsa_exception_fp_ieee_overflow 0
		.amdhsa_exception_fp_ieee_underflow 0
		.amdhsa_exception_fp_ieee_inexact 0
		.amdhsa_exception_int_div_zero 0
	.end_amdhsa_kernel

amdhsa.kernels:
  - .agpr_count:     0
    .args:
      - .offset:         0
        .size:           136
        .value_kind:     by_value
      - .offset:         136
        .size:           4
        .value_kind:     hidden_block_count_x
      - .offset:         140
        .size:           4
        .value_kind:     hidden_block_count_y
      - .offset:         144
        .size:           4
        .value_kind:     hidden_block_count_z
      - .offset:         148
        .size:           2
        .value_kind:     hidden_group_size_x
      - .offset:         150
        .size:           2
        .value_kind:     hidden_group_size_y
      - .offset:         152
        .size:           2
        .value_kind:     hidden_group_size_z
      - .offset:         154
        .size:           2
        .value_kind:     hidden_remainder_x
      - .offset:         156
        .size:           2
        .value_kind:     hidden_remainder_y
      - .offset:         158
        .size:           2
        .value_kind:     hidden_remainder_z
      - .offset:         176
        .size:           8
        .value_kind:     hidden_global_offset_x
      - .offset:         184
        .size:           8
        .value_kind:     hidden_global_offset_y
      - .offset:         192
        .size:           8
        .value_kind:     hidden_global_offset_z
      - .offset:         200
        .size:           2
        .value_kind:     hidden_grid_dims
      - .offset:         256
        .size:           4
        .value_kind:     hidden_dynamic_lds_size
    .group_segment_fixed_size: 0
    .kernarg_segment_align: 8
    .kernarg_segment_size: 392
    .language:       OpenCL C
    .language_version:
      - 2
      - 0
    .max_flat_workgroup_size: 512
    .name:           _Z14fwd_megakernel4Args
    .private_segment_fixed_size: 0
    .sgpr_count:     108
    .sgpr_spill_count: 26
    .symbol:         _Z14fwd_megakernel4Args.kd
    .uniform_work_group_size: 1
    .uses_dynamic_stack: false
    .vgpr_count:     256
    .vgpr_spill_count: 0
    .wavefront_size: 64
